# prompt attention: static s_setprio 1 for waves 4-7 over the unit loop (reset at exit), on top of v020
# baseline (speedup 1.0000x reference)
; __device__ __forceinline__ void phase_attn(Frame& F, const Params& p, int j) {
;     ...
;     const int lane = F.lane, fr = lane & 15, fq = lane >> 4;
;     const bf16_t* QN = F.HN;
;     constexpr int KSTR = 144, VSTR = 400, VOFF = 208 * KSTR;
;     const int vcu = (F.G & 7) == 0 ? (F.bid & 7) * (F.G >> 3) + (F.bid >> 3) : F.bid;
;     for (int u = vcu; u < 512; u += F.G) {
;         const int blk = u & 63, bk = u >> 6, b = bk >> 2, kvh = bk & 3, h = kvh * 8 + F.wave;
;         const float sink = p.in[14][j * 32 + h];
;         const int q_lo = blk == 0 ? 0 : 80 + 64 * (blk - 1), nmt = blk == 0 ? 5 : 4;
;         const int k_lo = q_lo - 128 > 0 ? q_lo - 128 : 0, nk = q_lo + 16 * nmt - k_lo;
;         const bf16_t* Kb = F.KN + ((size_t)bk * LP + k_lo) * 64;
;         const bf16_t* Vb = F.VT + (size_t)bk * 64 * VT_PITCH + k_lo;
;         bf16x8 qfa[5][2];
; #pragma unroll
;         for (int mt = 0; mt < 5; ++mt) { const int mm = mt < nmt ? mt : 0; const bf16_t* qp = QN + (size_t)prow(b, q_lo + 16 * mm + fr) * D + h * 64 + fq * 8;
;             qfa[mt][0] = *(const bf16x8*)qp; qfa[mt][1] = *(const bf16x8*)(qp + 32); }
.LBB0_1295:
	v_lshlrev_b32_e32 v46, 2, v47
	v_sub_u32_e32 v5, v46, v126
	v_lshlrev_b32_e32 v2, 3, v47
	v_and_b32_e32 v3, 48, v42
	v_cmp_lt_i32_e32 vcc, v215, v210
	v_cmp_lt_u32_e64 s[4:5], s42, v5
	v_mul_u32_u24_e32 v5, 0x190, v126
	v_ashrrev_i32_e32 v43, 31, v42
	v_readlane_b32 s10, v254, 51
	v_cndmask_b32_e32 v4, v208, v215, vcc
	v_cmp_lt_i32_e32 vcc, v216, v210
	v_add_u32_e32 v48, 0, v3
	v_add3_u32 v70, 0, v2, v5
	v_lshlrev_b64 v[2:3], 4, v[42:43]
	v_readlane_b32 s11, v254, 52
	v_readlane_b32 s2, v254, 20
	v_lshlrev_b32_e32 v67, 2, v4
	v_cndmask_b32_e32 v4, v208, v216, vcc
	v_lshlrev_b32_e32 v71, 4, v42
	v_lshl_add_u64 v[50:51], s[10:11], 0, v[2:3]
	v_readlane_b32 s10, v255, 39
	v_lshlrev_b32_e32 v168, 4, v47
	v_readlane_b32 s3, v254, 21
	v_lshlrev_b32_e32 v68, 2, v4
	v_sub_u32_e32 v4, v126, v46
	v_add_u32_e32 v43, s10, v71
	v_readlane_b32 s10, v254, 53
	v_lshl_add_u64 v[44:45], s[2:3], 0, v[168:169]
	v_cmp_gt_u32_e64 s[2:3], s91, v4
	v_mul_u32_u24_e32 v6, 0x90, v126
	v_add_u32_e32 v7, -2, v4
	v_add_u32_e32 v4, -3, v4
	v_readlane_b32 s11, v254, 54
	v_or_b32_e32 v49, 0x2020, v126
	v_or_b32_e32 v66, -16, v42
	v_or_b32_e32 v69, 64, v126
	v_cmp_gt_u32_e64 s[6:7], s91, v7
	v_cmp_gt_u32_e64 s[8:9], s91, v4
	v_lshl_add_u64 v[52:53], s[10:11], 0, v[2:3]
	v_add_u32_e32 v72, v48, v6
	s_cmp_ge_u32 s50, 4
	s_cbranch_scc0 .Lprio_attn
	s_setprio 1
.Lprio_attn:
	s_branch .LBB0_1297
.LBB0_1296:
	s_add_i32 s24, s24, s22
	s_cmpk_gt_i32 s24, 0x1ff
	s_cbranch_scc1 .LBB0_1304

; __device__ __forceinline__ void phase_attn(Frame& F, const Params& p, int j) {
;     ...
;     const int gw = F.bid * 8 + F.wave, NGW = F.G * 8;
;     const int goff = NGW >= 2 * NSAMP * 32 ? NGW - NSAMP * 32 : 0;
;     for (int task = gw - goff; task < NSAMP * 32; task += NGW) {
;         if (task < 0) continue;
;         const int b = task >> 5, h = task & 31, kvh = h >> 3;
;         const float sink = p.in[14][j * 32 + h];
;         const float* kb = F.out + O_KS + (size_t)(j * NSAMP + b) * 128 * 256 + kvh * 64;
;         const float* vb = F.out + O_VS + (size_t)(j * NSAMP + b) * 128 * 256 + kvh * 64;
;         const float* qp = F.QS + (size_t)b * D + h * 64;
;         float s0 = 0.f, s1 = 0.f;
;         { const f32x4 qv = *((const f32x4*)qp + (lane & 15));
;           f32x4 kk[32];
; #pragma unroll
;           for (int i = 0; i < 32; ++i) kk[i] = *((const f32x4*)(kb + (size_t)(4 * i + (lane >> 4)) * 256) + (lane & 15));
; #pragma unroll
;           for (int i = 0; i < 32; ++i) { float d = (qv.x * kk[i].x + qv.y * kk[i].y) + (qv.z * kk[i].z + qv.w * kk[i].w);
;               d += __shfl_xor(d, 1); d += __shfl_xor(d, 2); d += __shfl_xor(d, 4); d += __shfl_xor(d, 8);
;               const int key = 4 * i, tl = key & 63;
;               const float dv = __shfl(d, ((lane - tl) & 3) * 16);
;               if (lane >= tl && lane < tl + 4) { if (i < 16) s0 = dv; else s1 = dv; } } }
.LBB0_1304:
	s_setprio 0
	s_lshl_b32 s2, s23, 3
	s_lshl_b32 s59, s22, 3
	s_add_i32 s2, s2, s50
	s_sub_i32 s3, 0x400, s59
	s_cmpk_gt_i32 s22, 0xff
	s_cselect_b32 s3, s3, 0
	s_add_i32 s64, s2, s3
	s_cmpk_gt_i32 s64, 0x3ff
	s_cbranch_scc1 .LBB0_1312
	s_waitcnt vmcnt(16)
	v_and_b32_e32 v2, 63, v42
	v_lshlrev_b32_e32 v3, 4, v2
	v_and_b32_e32 v127, 48, v3
	v_lshlrev_b32_e32 v3, 5, v47
	v_cmp_gt_u32_e64 s[2:3], 32, v2
	v_cmp_gt_u32_e64 s[56:57], 16, v2
	v_cmp_gt_u32_e64 s[60:61], 4, v2
	v_and_b32_e32 v2, 60, v42
	s_mov_b64 s[88:89], s[72:73]
	v_and_b32_e32 v132, 32, v3
	v_lshlrev_b32_e32 v128, 10, v47
	v_mov_b32_e32 v129, v169
	v_cmp_eq_u32_e64 s[62:63], 4, v2
	v_cmp_eq_u32_e64 s[72:73], 8, v2
	v_cmp_eq_u32_e64 s[44:45], 12, v2
	v_cmp_eq_u32_e64 s[50:51], 16, v2
	v_cmp_eq_u32_e64 s[52:53], 20, v2
	v_cmp_eq_u32_e64 s[54:55], 24, v2
	v_cmp_eq_u32_e64 s[20:21], 28, v2
	v_cmp_eq_u32_e64 s[22:23], 32, v2
	v_cmp_eq_u32_e64 s[24:25], 36, v2
	v_cmp_eq_u32_e64 s[26:27], 40, v2
	v_cmp_eq_u32_e64 s[28:29], 44, v2
	v_cmp_eq_u32_e64 s[30:31], 48, v2
	v_cmp_eq_u32_e64 s[34:35], 52, v2
	v_cmp_eq_u32_e64 s[36:37], 56, v2
	v_cmp_eq_u32_e64 s[38:39], 60, v2
	v_lshlrev_b32_e32 v130, 15, v47
	v_mov_b32_e32 v131, v169
	s_branch .LBB0_1308
